# P3 loop: V-slot offset SALU pair replaces the s_nop pad in the first QK chain gap
# speedup vs baseline: 1.0098x; 1.0014x over previous
.LBB0_325:
	s_waitcnt lgkmcnt(4)
	v_mfma_f32_32x32x16_bf16 v[96:111], v[80:83], v[144:147], v[64:79]
	v_mfma_f32_32x32x16_bf16 v[96:111], v[202:205], v[140:143], v[96:111]
	s_add_i32 s4, s100, 64
	v_cvt_f32_i32_e32 v156, s4
	v_add_f32_e32 v156, v255, v156
	v_fma_f32 v254, v208, v156, -v207
	s_add_i32 s3, s79, 0xfffe8000
	s_and_b32 s3, s3, 0x18000
	v_mfma_f32_32x32x16_bf16 v[96:111], v[194:197], v[136:139], v[96:111]
	v_mov_b32_e32 v64, v254
	v_fmamk_f32 v65, v208, 0x3f800000, v254
	v_fmamk_f32 v66, v208, 0x40000000, v254
	v_fmamk_f32 v67, v208, 0x40400000, v254
	v_fmamk_f32 v68, v208, 0x41000000, v254
	v_fmamk_f32 v69, v208, 0x41100000, v254
	v_fmamk_f32 v70, v208, 0x41200000, v254
	v_fmamk_f32 v71, v208, 0x41300000, v254
	v_mfma_f32_32x32x16_bf16 v[96:111], v[186:189], v[132:135], v[96:111]
	v_fmamk_f32 v72, v208, 0x41800000, v254
	v_fmamk_f32 v73, v208, 0x41880000, v254
	v_fmamk_f32 v74, v208, 0x41900000, v254
	v_fmamk_f32 v75, v208, 0x41980000, v254
	v_fmamk_f32 v76, v208, 0x41c00000, v254
	v_fmamk_f32 v77, v208, 0x41c80000, v254
	v_fmamk_f32 v78, v208, 0x41d00000, v254
	v_fmamk_f32 v79, v208, 0x41d80000, v254
	v_add_u32_e32 v158, s3, v235
	v_add_u32_e32 v159, s3, v239
	v_add_u32_e32 v160, s3, v236
	v_add_u32_e32 v161, s3, v234
	ds_read_b64_tr_b16 v[182:183], v158 offset:32768
	ds_read_b64_tr_b16 v[184:185], v158 offset:34816
	ds_read_b64_tr_b16 v[178:179], v159 offset:32768
	ds_read_b64_tr_b16 v[180:181], v159 offset:34816
	ds_read_b64_tr_b16 v[148:149], v160 offset:32768
	ds_read_b64_tr_b16 v[150:151], v160 offset:34816
	ds_read_b64_tr_b16 v[152:153], v161 offset:32768
	ds_read_b64_tr_b16 v[154:155], v161 offset:34816
	s_waitcnt lgkmcnt(8)
	v_mfma_f32_32x32x16_bf16 v[80:95], v[198:201], v[144:147], v[64:79]
	v_exp_f32_e32 v96, v96
	v_exp_f32_e32 v97, v97
	v_exp_f32_e32 v98, v98
	v_exp_f32_e32 v99, v99
	v_mfma_f32_32x32x16_bf16 v[80:95], v[190:193], v[140:143], v[80:95]
	v_exp_f32_e32 v100, v100
	v_exp_f32_e32 v101, v101
	v_exp_f32_e32 v102, v102
	v_exp_f32_e32 v103, v103
	v_mfma_f32_32x32x16_bf16 v[80:95], v[246:249], v[136:139], v[80:95]
	v_exp_f32_e32 v104, v104
	v_exp_f32_e32 v105, v105
	v_exp_f32_e32 v106, v106
	v_exp_f32_e32 v107, v107
	v_mfma_f32_32x32x16_bf16 v[80:95], v[250:253], v[132:135], v[80:95]
	v_exp_f32_e32 v108, v108
	v_exp_f32_e32 v109, v109
	v_exp_f32_e32 v110, v110
	v_exp_f32_e32 v111, v111
	s_add_i32 s79, s79, 0x8000
	s_add_i32 s100, s100, 64
	s_nop 1
	s_cmp_le_i32 s72, s101
	s_cbranch_scc0 .Lmask_blk
